# G3->PEER seam also XCD-local (Q, H, X are quarter-local; the l==3 table-ready acquire is unaffected: those lines were never cached by the reading XCDs)
# speedup vs baseline: 1.1739x; 1.0128x over previous
.LBB0_812:
	s_andn2_saveexec_b64 s[4:5], s[4:5]
	s_cbranch_execz .LBB0_832
	s_mov_b64 s[4:5], exec
	v_readlane_b32 s98, v255, 63
	s_nop 0
	s_cmp_eq_u32 s98, 0
	s_cbranch_scc1 .Lbar_local_g3
	buffer_wbl2 sc1
	s_waitcnt lgkmcnt(0)
	s_waitcnt vmcnt(0)
	v_mbcnt_lo_u32_b32 v0, s4, 0
	v_mbcnt_hi_u32_b32 v0, s5, v0
	v_cmp_eq_u32_e32 vcc, 0, v0
	s_and_saveexec_b64 s[6:7], vcc
	s_cbranch_execz .LBB0_815
	s_bcnt1_i32_b64 s4, s[4:5]
	v_mov_b32_e32 v3, s4
	v_readlane_b32 s4, v254, 7
	v_readlane_b32 s5, v254, 8
	s_nop 4
	global_atomic_add v3, v1, v3, s[4:5] sc0
.LBB0_815:
	s_or_b64 exec, exec, s[6:7]
	s_waitcnt vmcnt(0)
	v_readfirstlane_b32 s4, v3
	v_sub_u32_e32 v4, 0, v2
	s_mov_b64 s[6:7], -1
	v_add_u32_e32 v3, s4, v0
	v_cvt_f32_u32_e32 v0, v2
	v_readlane_b32 s4, v254, 9
	v_readlane_b32 s5, v254, 10
	v_rcp_iflag_f32_e32 v0, v0
	s_nop 0
	v_mul_f32_e32 v0, 0x4f7ffffe, v0
	v_cvt_u32_f32_e32 v0, v0
	v_mul_lo_u32 v4, v4, v0
	v_mul_hi_u32 v4, v0, v4
	v_add_u32_e32 v0, v0, v4
	v_mul_hi_u32 v0, v3, v0
	v_mul_lo_u32 v4, v0, v2
	v_sub_u32_e32 v4, v3, v4
	v_cmp_ge_u32_e32 vcc, v4, v2
	v_add_u32_e32 v5, 1, v0
	v_add_u32_e32 v3, 1, v3
	v_cndmask_b32_e32 v0, v0, v5, vcc
	v_sub_u32_e32 v5, v4, v2
	v_cndmask_b32_e32 v4, v4, v5, vcc
	v_cmp_ge_u32_e32 vcc, v4, v2
	v_add_u32_e32 v4, 1, v0
	s_nop 0
	v_cndmask_b32_e32 v0, v0, v4, vcc
	v_mul_lo_u32 v4, v2, v0
	v_add_u32_e32 v2, v4, v2
	v_cmp_ne_u32_e32 vcc, v3, v2
	v_mov_b64_e32 v[2:3], s[4:5]
	s_and_saveexec_b64 s[4:5], vcc
	s_cbranch_execz .LBB0_827
	v_readlane_b32 s6, v254, 9
	v_readlane_b32 s7, v254, 10
	s_mov_b64 s[8:9], 0
	s_nop 3
	global_load_dword v2, v1, s[6:7] sc1
	s_waitcnt vmcnt(0)
	v_cmp_eq_u32_e32 vcc, v2, v0
	s_and_saveexec_b64 s[6:7], vcc
	s_cbranch_execz .LBB0_826
	s_mov_b32 s20, 1
	s_branch .LBB0_819

.Lbar_local_g3:
	s_mov_b64 s[4:5], exec
	v_mbcnt_lo_u32_b32 v0, s4, 0
	v_mbcnt_hi_u32_b32 v0, s5, v0
	v_cmp_eq_u32_e32 vcc, 0, v0
	s_waitcnt vmcnt(0)
	s_and_saveexec_b64 s[6:7], vcc
	s_cbranch_execz .LBB0_831
	s_bcnt1_i32_b64 s4, s[4:5]
	v_mov_b32_e32 v0, s4
	v_mov_b32_e32 v2, 0x2000
	global_atomic_add v2, v0, s[2:3] offset:1024
.LBB0_831:
	s_or_b64 exec, exec, s[6:7]
	s_waitcnt vmcnt(0)
